# FFT phase reads its (read-once) channel-DFT input with sc1 loads
# speedup vs baseline: 1.0359x; 1.0004x over previous
; #define GAS __attribute__((address_space(1)))
; #define LAS __attribute__((address_space(3)))
; __device__ __forceinline__ void fft_phase(Frame& F, const bf16* Yc, bf16* Y) {
;     ...
;     for (int item = F.vcu; item < 256; item += F.G) {
;         const int b = item >> 7, g = (item >> 4) & 7, q4 = item & 15;
;         const bf16* src = Yc + ((size_t)(b * 128 + g * 16 + q4) * SEQ + t) * 8;
;         LAS unsigned char* lt = buf + 16 * (t + (t >> 5));
; #pragma unroll 1
;         for (int i = 0; i < 16; i += 8) { v4u v[8];
; #pragma unroll
;             for (int j = 0; j < 8; ++j) v[j] = *(const GAS v4u*)(src + (size_t)(512 * (i + j)) * 8);
; #pragma unroll
;             for (int j = 0; j < 8; ++j) *(LAS v4u*)(lt + 8464 * (i + j)) = v[j]; }
.LBB0_195:
	v_cndmask_b32_e64 v4, 0, 1, s[4:5]
	s_lshl_b32 s0, s2, 12
	s_or_b32 s12, s0, 0x1000
	v_cmp_ne_u32_e32 vcc, 1, v4
	v_lshl_add_u64 v[4:5], s[0:1], 1, v[2:3]
	s_mov_b32 s13, s1
	s_or_b32 s14, s0, 0x2000
	global_load_dwordx4 v[4:7], v[4:5], off sc1
	v_lshl_add_u64 v[8:9], s[12:13], 1, v[2:3]
	s_mov_b32 s15, s1
	s_or_b32 s18, s0, 0x3000
	global_load_dwordx4 v[138:141], v[8:9], off sc1
	v_lshl_add_u64 v[8:9], s[14:15], 1, v[2:3]
	s_mov_b32 s19, s1
	s_or_b32 s20, s0, 0x4000
	global_load_dwordx4 v[142:145], v[8:9], off sc1
	v_lshl_add_u64 v[8:9], s[18:19], 1, v[2:3]
	s_mov_b32 s21, s1
	s_or_b32 s22, s0, 0x5000
	global_load_dwordx4 v[146:149], v[8:9], off sc1
	v_lshl_add_u64 v[8:9], s[20:21], 1, v[2:3]
	s_mov_b32 s23, s1
	s_or_b32 s6, s0, 0x6000
	global_load_dwordx4 v[150:153], v[8:9], off sc1
	v_lshl_add_u64 v[8:9], s[22:23], 1, v[2:3]
	s_mov_b32 s7, s1
	s_or_b32 s4, s0, 0x7000
	global_load_dwordx4 v[154:157], v[8:9], off sc1
	v_lshl_add_u64 v[8:9], s[6:7], 1, v[2:3]
	s_mov_b32 s5, s1
	global_load_dwordx4 v[158:161], v[8:9], off sc1
	v_lshl_add_u64 v[8:9], s[4:5], 1, v[2:3]
	global_load_dwordx4 v[162:165], v[8:9], off sc1
	s_mul_i32 s0, s2, 0x2110
	v_add_u32_e32 v8, s0, v166
	s_mov_b32 s2, 8
	s_mov_b64 s[4:5], 0
	s_and_b64 vcc, exec, vcc
	s_waitcnt vmcnt(0)
	ds_write_b128 v8, v[4:7]
	s_waitcnt vmcnt(6)
	ds_write_b128 v8, v[138:141] offset:8464
	s_waitcnt vmcnt(5)
	ds_write_b128 v8, v[142:145] offset:16928
	s_waitcnt vmcnt(4)
	ds_write_b128 v8, v[146:149] offset:25392
	s_waitcnt vmcnt(3)
	ds_write_b128 v8, v[150:153] offset:33856
	s_waitcnt vmcnt(2)
	ds_write_b128 v8, v[154:157] offset:42320
	s_waitcnt vmcnt(1)
	ds_write_b128 v8, v[158:161] offset:50784
	s_waitcnt vmcnt(0)
	ds_write_b128 v8, v[162:165] offset:59248
	s_cbranch_vccz .LBB0_195
	s_mov_b32 s0, 0
	s_mov_b64 s[4:5], -1
	s_waitcnt lgkmcnt(0)
	s_barrier
